# P5 meta-row mini-GEMMs (waves gw<64) rewritten by hand: operand loads batched, two halves in flight
# baseline (speedup 1.0000x reference)
.LBB0_862:
	v_readlane_b32 s4, v240, 2
	v_readlane_b32 s5, v240, 3
	s_cmp_lt_i32 s4, 6
	s_cselect_b64 s[4:5], -1, 0
	s_and_b64 s[0:1], s[4:5], s[0:1]
	s_andn2_b64 vcc, exec, s[0:1]
	s_cbranch_vccnz .LBB0_900
	v_readlane_b32 s4, v240, 26
	s_cmp_gt_i32 s4, 63
	v_readlane_b32 s5, v240, 27
	s_cbranch_scc1 .LBB0_865
	v_readlane_b32 s4, v240, 26
	s_lshl_b32 s3, s4, 4
	v_and_b32_e32 v144, 15, v190
	v_and_b32_e32 v145, 48, v190
	v_lshl_or_b32 v146, v144, 10, v145
	v_or_b32_e32 v147, s3, v144
	v_lshl_or_b32 v147, v147, 10, v145
	v_add_u32_e32 v8, 0x15900000, v146
	v_add_u32_e32 v9, 0xa80000, v147
	v_add_u32_e32 v138, 0x10700000, v146
	v_add_u32_e32 v139, 0xd00000, v147
	v_lshrrev_b32_e32 v148, 2, v145
	v_add_u32_e32 v148, s3, v148
	v_lshl_add_u32 v140, v144, 11, v148
	v_add_u32_e32 v140, 0xa500000, v140
	v_lshlrev_b32_e32 v149, 1, v148
	v_lshl_add_u32 v141, v144, 11, v149
	v_add_u32_e32 v141, 0x3d4000, v141
	global_load_dword v142, v140, s[94:95]
	global_load_dword v143, v140, s[94:95] offset:1024
	global_load_dwordx4 v[42:45], v9, s[94:95]
	global_load_dwordx4 v[10:13], v8, s[94:95]
	global_load_dwordx4 v[46:49], v9, s[94:95] offset:64
	global_load_dwordx4 v[14:17], v8, s[94:95] offset:64
	global_load_dwordx4 v[50:53], v9, s[94:95] offset:128
	global_load_dwordx4 v[18:21], v8, s[94:95] offset:128
	global_load_dwordx4 v[54:57], v9, s[94:95] offset:192
	global_load_dwordx4 v[22:25], v8, s[94:95] offset:192
	global_load_dwordx4 v[58:61], v9, s[94:95] offset:256
	global_load_dwordx4 v[26:29], v8, s[94:95] offset:256
	global_load_dwordx4 v[62:65], v9, s[94:95] offset:320
	global_load_dwordx4 v[30:33], v8, s[94:95] offset:320
	global_load_dwordx4 v[66:69], v9, s[94:95] offset:384
	global_load_dwordx4 v[34:37], v8, s[94:95] offset:384
	global_load_dwordx4 v[70:73], v9, s[94:95] offset:448
	global_load_dwordx4 v[38:41], v8, s[94:95] offset:448
	global_load_dwordx4 v[106:109], v9, s[94:95] offset:512
	global_load_dwordx4 v[74:77], v8, s[94:95] offset:512
	global_load_dwordx4 v[110:113], v9, s[94:95] offset:576
	global_load_dwordx4 v[78:81], v8, s[94:95] offset:576
	global_load_dwordx4 v[114:117], v9, s[94:95] offset:640
	global_load_dwordx4 v[82:85], v8, s[94:95] offset:640
	global_load_dwordx4 v[118:121], v9, s[94:95] offset:704
	global_load_dwordx4 v[86:89], v8, s[94:95] offset:704
	global_load_dwordx4 v[122:125], v9, s[94:95] offset:768
	global_load_dwordx4 v[90:93], v8, s[94:95] offset:768
	global_load_dwordx4 v[126:129], v9, s[94:95] offset:832
	global_load_dwordx4 v[94:97], v8, s[94:95] offset:832
	global_load_dwordx4 v[130:133], v9, s[94:95] offset:896
	global_load_dwordx4 v[98:101], v8, s[94:95] offset:896
	global_load_dwordx4 v[134:137], v9, s[94:95] offset:960
	global_load_dwordx4 v[102:105], v8, s[94:95] offset:960
	v_mov_b32_e32 v0, 0
	v_mov_b32_e32 v1, 0
	v_mov_b32_e32 v2, 0
	v_mov_b32_e32 v3, 0
	v_mov_b32_e32 v4, 0
	v_mov_b32_e32 v5, 0
	v_mov_b32_e32 v6, 0
	v_mov_b32_e32 v7, 0
	s_nop 1
	s_waitcnt vmcnt(16)
	v_mfma_f32_16x16x32_bf16 v[0:3], v[42:45], v[10:13], v[0:3]
	v_mfma_f32_16x16x32_bf16 v[0:3], v[46:49], v[14:17], v[0:3]
	v_mfma_f32_16x16x32_bf16 v[0:3], v[50:53], v[18:21], v[0:3]
	v_mfma_f32_16x16x32_bf16 v[0:3], v[54:57], v[22:25], v[0:3]
	v_mfma_f32_16x16x32_bf16 v[0:3], v[58:61], v[26:29], v[0:3]
	v_mfma_f32_16x16x32_bf16 v[0:3], v[62:65], v[30:33], v[0:3]
	v_mfma_f32_16x16x32_bf16 v[0:3], v[66:69], v[34:37], v[0:3]
	v_mfma_f32_16x16x32_bf16 v[0:3], v[70:73], v[38:41], v[0:3]
	global_load_dwordx4 v[42:45], v139, s[94:95]
	global_load_dwordx4 v[10:13], v138, s[94:95]
	global_load_dwordx4 v[46:49], v139, s[94:95] offset:64
	global_load_dwordx4 v[14:17], v138, s[94:95] offset:64
	global_load_dwordx4 v[50:53], v139, s[94:95] offset:128
	global_load_dwordx4 v[18:21], v138, s[94:95] offset:128
	global_load_dwordx4 v[54:57], v139, s[94:95] offset:192
	global_load_dwordx4 v[22:25], v138, s[94:95] offset:192
	global_load_dwordx4 v[58:61], v139, s[94:95] offset:256
	global_load_dwordx4 v[26:29], v138, s[94:95] offset:256
	global_load_dwordx4 v[62:65], v139, s[94:95] offset:320
	global_load_dwordx4 v[30:33], v138, s[94:95] offset:320
	global_load_dwordx4 v[66:69], v139, s[94:95] offset:384
	global_load_dwordx4 v[34:37], v138, s[94:95] offset:384
	global_load_dwordx4 v[70:73], v139, s[94:95] offset:448
	global_load_dwordx4 v[38:41], v138, s[94:95] offset:448
	s_waitcnt vmcnt(16)
	v_mfma_f32_16x16x32_bf16 v[0:3], v[106:109], v[74:77], v[0:3]
	v_mfma_f32_16x16x32_bf16 v[0:3], v[110:113], v[78:81], v[0:3]
	v_mfma_f32_16x16x32_bf16 v[0:3], v[114:117], v[82:85], v[0:3]
	v_mfma_f32_16x16x32_bf16 v[0:3], v[118:121], v[86:89], v[0:3]
	v_mfma_f32_16x16x32_bf16 v[0:3], v[122:125], v[90:93], v[0:3]
	v_mfma_f32_16x16x32_bf16 v[0:3], v[126:129], v[94:97], v[0:3]
	v_mfma_f32_16x16x32_bf16 v[0:3], v[130:133], v[98:101], v[0:3]
	v_mfma_f32_16x16x32_bf16 v[0:3], v[134:137], v[102:105], v[0:3]
	global_load_dwordx4 v[106:109], v139, s[94:95] offset:512
	global_load_dwordx4 v[74:77], v138, s[94:95] offset:512
	global_load_dwordx4 v[110:113], v139, s[94:95] offset:576
	global_load_dwordx4 v[78:81], v138, s[94:95] offset:576
	global_load_dwordx4 v[114:117], v139, s[94:95] offset:640
	global_load_dwordx4 v[82:85], v138, s[94:95] offset:640
	global_load_dwordx4 v[118:121], v139, s[94:95] offset:704
	global_load_dwordx4 v[86:89], v138, s[94:95] offset:704
	global_load_dwordx4 v[122:125], v139, s[94:95] offset:768
	global_load_dwordx4 v[90:93], v138, s[94:95] offset:768
	global_load_dwordx4 v[126:129], v139, s[94:95] offset:832
	global_load_dwordx4 v[94:97], v138, s[94:95] offset:832
	global_load_dwordx4 v[130:133], v139, s[94:95] offset:896
	global_load_dwordx4 v[98:101], v138, s[94:95] offset:896
	global_load_dwordx4 v[134:137], v139, s[94:95] offset:960
	global_load_dwordx4 v[102:105], v138, s[94:95] offset:960
	s_waitcnt vmcnt(16)
	v_mfma_f32_16x16x32_bf16 v[4:7], v[42:45], v[10:13], v[4:7]
	v_mfma_f32_16x16x32_bf16 v[4:7], v[46:49], v[14:17], v[4:7]
	v_mfma_f32_16x16x32_bf16 v[4:7], v[50:53], v[18:21], v[4:7]
	v_mfma_f32_16x16x32_bf16 v[4:7], v[54:57], v[22:25], v[4:7]
	v_mfma_f32_16x16x32_bf16 v[4:7], v[58:61], v[26:29], v[4:7]
	v_mfma_f32_16x16x32_bf16 v[4:7], v[62:65], v[30:33], v[4:7]
	v_mfma_f32_16x16x32_bf16 v[4:7], v[66:69], v[34:37], v[4:7]
	v_mfma_f32_16x16x32_bf16 v[4:7], v[70:73], v[38:41], v[4:7]
	s_waitcnt vmcnt(0)
	v_mfma_f32_16x16x32_bf16 v[4:7], v[106:109], v[74:77], v[4:7]
	v_mfma_f32_16x16x32_bf16 v[4:7], v[110:113], v[78:81], v[4:7]
	v_mfma_f32_16x16x32_bf16 v[4:7], v[114:117], v[82:85], v[4:7]
	v_mfma_f32_16x16x32_bf16 v[4:7], v[118:121], v[86:89], v[4:7]
	v_mfma_f32_16x16x32_bf16 v[4:7], v[122:125], v[90:93], v[4:7]
	v_mfma_f32_16x16x32_bf16 v[4:7], v[126:129], v[94:97], v[4:7]
	v_mfma_f32_16x16x32_bf16 v[4:7], v[130:133], v[98:101], v[4:7]
	v_mfma_f32_16x16x32_bf16 v[4:7], v[134:137], v[102:105], v[4:7]
	v_cvt_f32_ubyte0_e32 v144, v142
	v_cvt_f32_ubyte1_e32 v145, v142
	v_cvt_f32_ubyte2_e32 v146, v142
	v_cvt_f32_ubyte3_e32 v147, v142
	v_cvt_f32_ubyte0_e32 v148, v143
	v_cvt_f32_ubyte1_e32 v149, v143
	v_cvt_f32_ubyte2_e32 v150, v143
	v_cvt_f32_ubyte3_e32 v151, v143
	v_max_f32_e32 v148, 1.0, v148
	v_max_f32_e32 v149, 1.0, v149
	v_max_f32_e32 v150, 1.0, v150
	v_max_f32_e32 v151, 1.0, v151
	s_nop 3
	v_mul_f32_e32 v148, v148, v4
	v_mul_f32_e32 v149, v149, v5
	v_mul_f32_e32 v150, v150, v6
	v_mul_f32_e32 v151, v151, v7
	v_fma_f32 v144, v144, v0, v148
	v_fma_f32 v145, v145, v1, v149
	v_fma_f32 v146, v146, v2, v150
	v_fma_f32 v147, v147, v3, v151
	v_mul_f32_e32 v144, 0x3b808081, v144
	v_mul_f32_e32 v145, 0x3b808081, v145
	v_mul_f32_e32 v146, 0x3b808081, v146
	v_mul_f32_e32 v147, 0x3b808081, v147
	v_cvt_pk_bf16_f32 v148, v144, v145
	v_cvt_pk_bf16_f32 v149, v146, v147
	global_store_dwordx2 v141, v[148:149], s[94:95]
